# conv phase cumulative dt*A: all 64 rows of a chunk loaded at once instead of four dependent rounds of 16
# baseline (speedup 1.0000x reference)
; #define GAS __attribute__((address_space(1)))
; __device__ __forceinline__ void phase_conv(const Params& P, int seg) {
;     ...
;     { const GAS float* dtv = (const GAS float*)(ws + WS_DT); GAS float* acv = (GAS float*)(ws + WS_ACUM); const int nch = RS / 64 + (seg == 0 ? 1 : 0);
;       for (int idx = gtid; idx < nch * 64; idx += NT) { const int c = idx >> 6, hd = idx & 63, r0 = (c < RS / 64) ? c * 64 : RS; const float Ah = -__expf(P.a_log[hd]); float acc = 0.f;
; #pragma unroll 16
;           for (int i = 0; i < 64; ++i) { acc += dtv[(size_t)(r0 + i) * 64 + hd] * Ah; acv[(size_t)(r0 + i) * 64 + hd] = acc; } } }
.LBB0_232:
	v_add_co_u32_e32 v16, vcc, 0x302e1000, v8
	s_nop 1
	v_addc_co_u32_e32 v17, vcc, 0, v9, vcc
	v_add_co_u32_e32 v14, vcc, 0x3b79e000, v8
	s_nop 1
	v_addc_co_u32_e32 v15, vcc, 0, v9, vcc
	s_mov_b64 s[16:17], 0x1000
	v_lshl_add_u64 v[18:19], v[16:17], 0, s[16:17]
	v_lshl_add_u64 v[24:25], v[14:15], 0, s[16:17]
	s_mov_b64 s[16:17], 0x2000
	v_lshl_add_u64 v[20:21], v[16:17], 0, s[16:17]
	v_lshl_add_u64 v[26:27], v[14:15], 0, s[16:17]
	s_mov_b64 s[16:17], 0x3000
	v_lshl_add_u64 v[22:23], v[16:17], 0, s[16:17]
	v_lshl_add_u64 v[28:29], v[14:15], 0, s[16:17]
	global_load_dword v40, v[16:17], off
	global_load_dword v41, v[16:17], off offset:256
	global_load_dword v42, v[16:17], off offset:512
	global_load_dword v43, v[16:17], off offset:768
	global_load_dword v44, v[16:17], off offset:1024
	global_load_dword v45, v[16:17], off offset:1280
	global_load_dword v46, v[16:17], off offset:1536
	global_load_dword v47, v[16:17], off offset:1792
	global_load_dword v48, v[16:17], off offset:2048
	global_load_dword v49, v[16:17], off offset:2304
	global_load_dword v50, v[16:17], off offset:2560
	global_load_dword v51, v[16:17], off offset:2816
	global_load_dword v52, v[16:17], off offset:3072
	global_load_dword v53, v[16:17], off offset:3328
	global_load_dword v54, v[16:17], off offset:3584
	global_load_dword v55, v[16:17], off offset:3840
	global_load_dword v56, v[18:19], off
	global_load_dword v57, v[18:19], off offset:256
	global_load_dword v58, v[18:19], off offset:512
	global_load_dword v59, v[18:19], off offset:768
	global_load_dword v60, v[18:19], off offset:1024
	global_load_dword v61, v[18:19], off offset:1280
	global_load_dword v62, v[18:19], off offset:1536
	global_load_dword v63, v[18:19], off offset:1792
	global_load_dword v64, v[18:19], off offset:2048
	global_load_dword v65, v[18:19], off offset:2304
	global_load_dword v66, v[18:19], off offset:2560
	global_load_dword v67, v[18:19], off offset:2816
	global_load_dword v68, v[18:19], off offset:3072
	global_load_dword v69, v[18:19], off offset:3328
	global_load_dword v70, v[18:19], off offset:3584
	global_load_dword v71, v[18:19], off offset:3840
	global_load_dword v72, v[20:21], off
	global_load_dword v73, v[20:21], off offset:256
	global_load_dword v74, v[20:21], off offset:512
	global_load_dword v75, v[20:21], off offset:768
	global_load_dword v76, v[20:21], off offset:1024
	global_load_dword v77, v[20:21], off offset:1280
	global_load_dword v78, v[20:21], off offset:1536
	global_load_dword v79, v[20:21], off offset:1792
	global_load_dword v80, v[20:21], off offset:2048
	global_load_dword v81, v[20:21], off offset:2304
	global_load_dword v82, v[20:21], off offset:2560
	global_load_dword v83, v[20:21], off offset:2816
	global_load_dword v84, v[20:21], off offset:3072
	global_load_dword v85, v[20:21], off offset:3328
	global_load_dword v86, v[20:21], off offset:3584
	global_load_dword v87, v[20:21], off offset:3840
	global_load_dword v88, v[22:23], off
	global_load_dword v89, v[22:23], off offset:256
	global_load_dword v90, v[22:23], off offset:512
	global_load_dword v91, v[22:23], off offset:768
	global_load_dword v92, v[22:23], off offset:1024
	global_load_dword v93, v[22:23], off offset:1280
	global_load_dword v94, v[22:23], off offset:1536
	global_load_dword v95, v[22:23], off offset:1792
	global_load_dword v96, v[22:23], off offset:2048
	global_load_dword v97, v[22:23], off offset:2304
	global_load_dword v98, v[22:23], off offset:2560
	global_load_dword v99, v[22:23], off offset:2816
	global_load_dword v100, v[22:23], off offset:3072
	global_load_dword v101, v[22:23], off offset:3328
	global_load_dword v102, v[22:23], off offset:3584
	global_load_dword v103, v[22:23], off offset:3840
	s_waitcnt vmcnt(63)
	v_fma_f32 v12, -v11, v40, v12
	global_store_dword v[14:15], v12, off
	s_waitcnt vmcnt(63)
	v_fma_f32 v12, -v11, v41, v12
	global_store_dword v[14:15], v12, off offset:256
	s_waitcnt vmcnt(63)
	v_fma_f32 v12, -v11, v42, v12
	global_store_dword v[14:15], v12, off offset:512
	s_waitcnt vmcnt(63)
	v_fma_f32 v12, -v11, v43, v12
	global_store_dword v[14:15], v12, off offset:768
	s_waitcnt vmcnt(63)
	v_fma_f32 v12, -v11, v44, v12
	global_store_dword v[14:15], v12, off offset:1024
	s_waitcnt vmcnt(63)
	v_fma_f32 v12, -v11, v45, v12
	global_store_dword v[14:15], v12, off offset:1280
	s_waitcnt vmcnt(63)
	v_fma_f32 v12, -v11, v46, v12
	global_store_dword v[14:15], v12, off offset:1536
	s_waitcnt vmcnt(63)
	v_fma_f32 v12, -v11, v47, v12
	global_store_dword v[14:15], v12, off offset:1792
	s_waitcnt vmcnt(63)
	v_fma_f32 v12, -v11, v48, v12
	global_store_dword v[14:15], v12, off offset:2048
	s_waitcnt vmcnt(63)
	v_fma_f32 v12, -v11, v49, v12
	global_store_dword v[14:15], v12, off offset:2304
	s_waitcnt vmcnt(63)
	v_fma_f32 v12, -v11, v50, v12
	global_store_dword v[14:15], v12, off offset:2560
	s_waitcnt vmcnt(63)
	v_fma_f32 v12, -v11, v51, v12
	global_store_dword v[14:15], v12, off offset:2816
	s_waitcnt vmcnt(63)
	v_fma_f32 v12, -v11, v52, v12
	global_store_dword v[14:15], v12, off offset:3072
	s_waitcnt vmcnt(63)
	v_fma_f32 v12, -v11, v53, v12
	global_store_dword v[14:15], v12, off offset:3328
	s_waitcnt vmcnt(63)
; #define GAS __attribute__((address_space(1)))
; __device__ __forceinline__ void phase_conv(const Params& P, int seg) {
;     ...
;     { const GAS float* dtv = (const GAS float*)(ws + WS_DT); GAS float* acv = (GAS float*)(ws + WS_ACUM); const int nch = RS / 64 + (seg == 0 ? 1 : 0);
;       for (int idx = gtid; idx < nch * 64; idx += NT) { const int c = idx >> 6, hd = idx & 63, r0 = (c < RS / 64) ? c * 64 : RS; const float Ah = -__expf(P.a_log[hd]); float acc = 0.f;
; #pragma unroll 16
;           for (int i = 0; i < 64; ++i) { acc += dtv[(size_t)(r0 + i) * 64 + hd] * Ah; acv[(size_t)(r0 + i) * 64 + hd] = acc; } } }
	v_fma_f32 v12, -v11, v54, v12
	global_store_dword v[14:15], v12, off offset:3584
	s_waitcnt vmcnt(63)
	v_fma_f32 v12, -v11, v55, v12
	global_store_dword v[14:15], v12, off offset:3840
	s_waitcnt vmcnt(63)
	v_fma_f32 v12, -v11, v56, v12
	global_store_dword v[24:25], v12, off
	s_waitcnt vmcnt(63)
	v_fma_f32 v12, -v11, v57, v12
	global_store_dword v[24:25], v12, off offset:256
	s_waitcnt vmcnt(63)
	v_fma_f32 v12, -v11, v58, v12
	global_store_dword v[24:25], v12, off offset:512
	s_waitcnt vmcnt(63)
	v_fma_f32 v12, -v11, v59, v12
	global_store_dword v[24:25], v12, off offset:768
	s_waitcnt vmcnt(63)
	v_fma_f32 v12, -v11, v60, v12
	global_store_dword v[24:25], v12, off offset:1024
	s_waitcnt vmcnt(63)
	v_fma_f32 v12, -v11, v61, v12
	global_store_dword v[24:25], v12, off offset:1280
	s_waitcnt vmcnt(63)
	v_fma_f32 v12, -v11, v62, v12
	global_store_dword v[24:25], v12, off offset:1536
	s_waitcnt vmcnt(63)
	v_fma_f32 v12, -v11, v63, v12
	global_store_dword v[24:25], v12, off offset:1792
	s_waitcnt vmcnt(63)
	v_fma_f32 v12, -v11, v64, v12
	global_store_dword v[24:25], v12, off offset:2048
	s_waitcnt vmcnt(63)
	v_fma_f32 v12, -v11, v65, v12
	global_store_dword v[24:25], v12, off offset:2304
	s_waitcnt vmcnt(63)
	v_fma_f32 v12, -v11, v66, v12
	global_store_dword v[24:25], v12, off offset:2560
	s_waitcnt vmcnt(63)
	v_fma_f32 v12, -v11, v67, v12
	global_store_dword v[24:25], v12, off offset:2816
	s_waitcnt vmcnt(63)
	v_fma_f32 v12, -v11, v68, v12
	global_store_dword v[24:25], v12, off offset:3072
	s_waitcnt vmcnt(63)
	v_fma_f32 v12, -v11, v69, v12
	global_store_dword v[24:25], v12, off offset:3328
	s_waitcnt vmcnt(63)
	v_fma_f32 v12, -v11, v70, v12
	global_store_dword v[24:25], v12, off offset:3584
	s_waitcnt vmcnt(63)
	v_fma_f32 v12, -v11, v71, v12
	global_store_dword v[24:25], v12, off offset:3840
	s_waitcnt vmcnt(63)
	v_fma_f32 v12, -v11, v72, v12
	global_store_dword v[26:27], v12, off
	s_waitcnt vmcnt(63)
	v_fma_f32 v12, -v11, v73, v12
	global_store_dword v[26:27], v12, off offset:256
	s_waitcnt vmcnt(63)
	v_fma_f32 v12, -v11, v74, v12
	global_store_dword v[26:27], v12, off offset:512
	s_waitcnt vmcnt(63)
	v_fma_f32 v12, -v11, v75, v12
	global_store_dword v[26:27], v12, off offset:768
	s_waitcnt vmcnt(63)
	v_fma_f32 v12, -v11, v76, v12
	global_store_dword v[26:27], v12, off offset:1024
	s_waitcnt vmcnt(63)
	v_fma_f32 v12, -v11, v77, v12
	global_store_dword v[26:27], v12, off offset:1280
	s_waitcnt vmcnt(63)
	v_fma_f32 v12, -v11, v78, v12
	global_store_dword v[26:27], v12, off offset:1536
	s_waitcnt vmcnt(63)
	v_fma_f32 v12, -v11, v79, v12
	global_store_dword v[26:27], v12, off offset:1792
	s_waitcnt vmcnt(63)
	v_fma_f32 v12, -v11, v80, v12
	global_store_dword v[26:27], v12, off offset:2048
	s_waitcnt vmcnt(63)
	v_fma_f32 v12, -v11, v81, v12
	global_store_dword v[26:27], v12, off offset:2304
	s_waitcnt vmcnt(63)
	v_fma_f32 v12, -v11, v82, v12
	global_store_dword v[26:27], v12, off offset:2560
	s_waitcnt vmcnt(63)
	v_fma_f32 v12, -v11, v83, v12
	global_store_dword v[26:27], v12, off offset:2816
	s_waitcnt vmcnt(63)
	v_fma_f32 v12, -v11, v84, v12
	global_store_dword v[26:27], v12, off offset:3072
	s_waitcnt vmcnt(63)
	v_fma_f32 v12, -v11, v85, v12
	global_store_dword v[26:27], v12, off offset:3328
	s_waitcnt vmcnt(63)
	v_fma_f32 v12, -v11, v86, v12
	global_store_dword v[26:27], v12, off offset:3584
	s_waitcnt vmcnt(63)
	v_fma_f32 v12, -v11, v87, v12
	global_store_dword v[26:27], v12, off offset:3840
	s_waitcnt vmcnt(63)
	v_fma_f32 v12, -v11, v88, v12
	global_store_dword v[28:29], v12, off
	s_waitcnt vmcnt(63)
	v_fma_f32 v12, -v11, v89, v12
	global_store_dword v[28:29], v12, off offset:256
	s_waitcnt vmcnt(63)
	v_fma_f32 v12, -v11, v90, v12
	global_store_dword v[28:29], v12, off offset:512
	s_waitcnt vmcnt(63)
	v_fma_f32 v12, -v11, v91, v12
	global_store_dword v[28:29], v12, off offset:768
	s_waitcnt vmcnt(63)
	v_fma_f32 v12, -v11, v92, v12
	global_store_dword v[28:29], v12, off offset:1024
	s_waitcnt vmcnt(63)
	v_fma_f32 v12, -v11, v93, v12
	global_store_dword v[28:29], v12, off offset:1280
	s_waitcnt vmcnt(63)
	v_fma_f32 v12, -v11, v94, v12
	global_store_dword v[28:29], v12, off offset:1536
	s_waitcnt vmcnt(63)
	v_fma_f32 v12, -v11, v95, v12
	global_store_dword v[28:29], v12, off offset:1792
	s_waitcnt vmcnt(63)
	v_fma_f32 v12, -v11, v96, v12
	global_store_dword v[28:29], v12, off offset:2048
	s_waitcnt vmcnt(63)
	v_fma_f32 v12, -v11, v97, v12
	global_store_dword v[28:29], v12, off offset:2304
	s_waitcnt vmcnt(63)
	v_fma_f32 v12, -v11, v98, v12
	global_store_dword v[28:29], v12, off offset:2560
	s_waitcnt vmcnt(63)
	v_fma_f32 v12, -v11, v99, v12
	global_store_dword v[28:29], v12, off offset:2816
	s_waitcnt vmcnt(63)
	v_fma_f32 v12, -v11, v100, v12
	global_store_dword v[28:29], v12, off offset:3072
	s_waitcnt vmcnt(63)
	v_fma_f32 v12, -v11, v101, v12
	global_store_dword v[28:29], v12, off offset:3328
	s_waitcnt vmcnt(63)
	v_fma_f32 v12, -v11, v102, v12
	global_store_dword v[28:29], v12, off offset:3584
	s_waitcnt vmcnt(63)
	v_fma_f32 v12, -v11, v103, v12
	global_store_dword v[28:29], v12, off offset:3840
	v_add_u32_e32 v10, s20, v10
	v_cmp_le_i32_e32 vcc, s9, v10
	s_or_b64 s[14:15], vcc, s[14:15]
	s_andn2_b64 exec, exec, s[14:15]
	s_cbranch_execnz .LBB0_231
